# speedup vs baseline: 1.0315x; 1.0074x over previous
.LBB0_561:
	v_cvt_pk_bf16_f32 v102, v88, v89
	v_cvt_pk_bf16_f32 v103, v86, v87
	v_cvt_pk_bf16_f32 v104, v92, v93
	v_cvt_pk_bf16_f32 v105, v90, v91
	s_lshr_b32 s32, s4, 1
	v_add_u32_e32 v251, s32, v99
	s_add_i32 s4, s4, 64
	v_cvt_pk_bf16_f32 v82, v82, v83
	v_cvt_pk_bf16_f32 v83, v78, v79
	v_cvt_pk_bf16_f32 v84, v84, v85
	v_cvt_pk_bf16_f32 v85, v80, v81
	ds_write_b128 v251, v[102:105]
	ds_write_b128 v251, v[82:85] offset:16
	s_cmpk_lg_i32 s4, 0x100
	v_lshl_add_u64 v[76:77], v[76:77], 0, 32
	s_cbranch_scc0 .LBB0_565

.LBB0_565:
	v_and_b32_e32 v84, 63, v170
	v_lshrrev_b32_e32 v85, 3, v84
	v_sub_u32_e32 v85, v85, v84
	v_and_b32_e32 v84, 7, v84
	v_lshlrev_b32_e32 v84, 4, v84
	v_mul_i32_i24_e32 v78, 0x1400, v85
	v_add_u32_e32 v78, v78, v84
	v_add_u32_e32 v78, 0xffffff80, v78
	v_mul_i32_i24_e32 v85, 0x110, v85
	v_add3_u32 v85, v85, v84, v99
	s_waitcnt lgkmcnt(0)
	ds_read_b128 v[72:75], v85 offset:0
	v_mov_b32_e32 v80, v78
	v_ashrrev_i32_e32 v81, 31, v80
	v_lshl_add_u64 v[82:83], v[80:81], 0, v[76:77]
	s_waitcnt lgkmcnt(0)
	global_store_dwordx4 v[82:83], v[72:75], off
	s_nop 1
	ds_read_b128 v[72:75], v85 offset:2176
	v_add_u32_e32 v80, 0xa000, v78
	v_ashrrev_i32_e32 v81, 31, v80
	v_lshl_add_u64 v[82:83], v[80:81], 0, v[76:77]
	s_waitcnt lgkmcnt(0)
	global_store_dwordx4 v[82:83], v[72:75], off
	s_nop 1
	ds_read_b128 v[72:75], v85 offset:4352
	v_add_u32_e32 v80, 0x14000, v78
	v_ashrrev_i32_e32 v81, 31, v80
	v_lshl_add_u64 v[82:83], v[80:81], 0, v[76:77]
	s_waitcnt lgkmcnt(0)
	global_store_dwordx4 v[82:83], v[72:75], off
	s_nop 1
	ds_read_b128 v[72:75], v85 offset:6528
	v_add_u32_e32 v80, 0x1e000, v78
	v_ashrrev_i32_e32 v81, 31, v80
	v_lshl_add_u64 v[82:83], v[80:81], 0, v[76:77]
	s_waitcnt lgkmcnt(0)
	global_store_dwordx4 v[82:83], v[72:75], off
	s_nop 1
	ds_read_b128 v[72:75], v85 offset:8704
	v_add_u32_e32 v80, 0x28000, v78
	v_ashrrev_i32_e32 v81, 31, v80
	v_lshl_add_u64 v[82:83], v[80:81], 0, v[76:77]
	s_waitcnt lgkmcnt(0)
	global_store_dwordx4 v[82:83], v[72:75], off
	s_nop 1
	ds_read_b128 v[72:75], v85 offset:10880
	v_add_u32_e32 v80, 0x32000, v78
	v_ashrrev_i32_e32 v81, 31, v80
	v_lshl_add_u64 v[82:83], v[80:81], 0, v[76:77]
	s_waitcnt lgkmcnt(0)
	global_store_dwordx4 v[82:83], v[72:75], off
	s_nop 1
	ds_read_b128 v[72:75], v85 offset:13056
	v_add_u32_e32 v80, 0x3c000, v78
	v_ashrrev_i32_e32 v81, 31, v80
	v_lshl_add_u64 v[82:83], v[80:81], 0, v[76:77]
	s_waitcnt lgkmcnt(0)
	global_store_dwordx4 v[82:83], v[72:75], off
	s_nop 1
	ds_read_b128 v[72:75], v85 offset:15232
	v_add_u32_e32 v80, 0x46000, v78
	v_ashrrev_i32_e32 v81, 31, v80
	v_lshl_add_u64 v[82:83], v[80:81], 0, v[76:77]
	s_waitcnt lgkmcnt(0)
	global_store_dwordx4 v[82:83], v[72:75], off
	s_nop 1
	s_mov_b64 s[4:5], 0

.LBB0_575:
	v_cvt_pk_bf16_f32 v14, v14, v15
	v_cvt_pk_bf16_f32 v15, v10, v11
	v_lshl_add_u64 v[10:11], v[8:9], 0, s[6:7]
	v_add_u32_e32 v251, s6, v1
	s_add_u32 s6, s6, 32
	s_addc_u32 s7, s7, 0
	v_cvt_pk_bf16_f32 v30, v20, v21
	v_cvt_pk_bf16_f32 v31, v18, v19
	v_cvt_pk_bf16_f32 v32, v24, v25
	v_cvt_pk_bf16_f32 v33, v22, v23
	s_cmpk_eq_i32 s6, 0x80
	v_add_u32_e32 v28, 64, v28
	v_cvt_pk_bf16_f32 v16, v16, v17
	v_cvt_pk_bf16_f32 v17, v12, v13
	ds_write_b128 v251, v[30:33]
	ds_write_b128 v251, v[14:17] offset:16
	s_cbranch_scc1 .LBB0_578

.LBB0_578:
	v_and_b32_e32 v16, 63, v170
	v_lshrrev_b32_e32 v17, 3, v16
	v_sub_u32_e32 v17, v17, v16
	v_and_b32_e32 v16, 7, v16
	v_lshlrev_b32_e32 v16, 4, v16
	v_mul_i32_i24_e32 v10, 0x1400, v17
	v_add_u32_e32 v10, v10, v16
	v_mul_i32_i24_e32 v17, 0x110, v17
	v_add3_u32 v17, v17, v16, v1
	s_waitcnt lgkmcnt(0)
	ds_read_b128 v[4:7], v17 offset:0
	v_mov_b32_e32 v12, v10
	v_ashrrev_i32_e32 v13, 31, v12
	v_lshl_add_u64 v[14:15], v[12:13], 0, v[8:9]
	s_waitcnt lgkmcnt(0)
	global_store_dwordx4 v[14:15], v[4:7], off offset:128
	s_nop 1
	ds_read_b128 v[4:7], v17 offset:2176
	v_add_u32_e32 v12, 0xa000, v10
	v_ashrrev_i32_e32 v13, 31, v12
	v_lshl_add_u64 v[14:15], v[12:13], 0, v[8:9]
	s_waitcnt lgkmcnt(0)
	global_store_dwordx4 v[14:15], v[4:7], off offset:128
	s_nop 1
	ds_read_b128 v[4:7], v17 offset:4352
	v_add_u32_e32 v12, 0x14000, v10
	v_ashrrev_i32_e32 v13, 31, v12
	v_lshl_add_u64 v[14:15], v[12:13], 0, v[8:9]
	s_waitcnt lgkmcnt(0)
	global_store_dwordx4 v[14:15], v[4:7], off offset:128
	s_nop 1
	ds_read_b128 v[4:7], v17 offset:6528
	v_add_u32_e32 v12, 0x1e000, v10
	v_ashrrev_i32_e32 v13, 31, v12
	v_lshl_add_u64 v[14:15], v[12:13], 0, v[8:9]
	s_waitcnt lgkmcnt(0)
	global_store_dwordx4 v[14:15], v[4:7], off offset:128
	s_nop 1
	ds_read_b128 v[4:7], v17 offset:8704
	v_add_u32_e32 v12, 0x28000, v10
	v_ashrrev_i32_e32 v13, 31, v12
	v_lshl_add_u64 v[14:15], v[12:13], 0, v[8:9]
	s_waitcnt lgkmcnt(0)
	global_store_dwordx4 v[14:15], v[4:7], off offset:128
	s_nop 1
	ds_read_b128 v[4:7], v17 offset:10880
	v_add_u32_e32 v12, 0x32000, v10
	v_ashrrev_i32_e32 v13, 31, v12
	v_lshl_add_u64 v[14:15], v[12:13], 0, v[8:9]
	s_waitcnt lgkmcnt(0)
	global_store_dwordx4 v[14:15], v[4:7], off offset:128
	s_nop 1
	ds_read_b128 v[4:7], v17 offset:13056
	v_add_u32_e32 v12, 0x3c000, v10
	v_ashrrev_i32_e32 v13, 31, v12
	v_lshl_add_u64 v[14:15], v[12:13], 0, v[8:9]
	s_waitcnt lgkmcnt(0)
	global_store_dwordx4 v[14:15], v[4:7], off offset:128
	s_nop 1
	ds_read_b128 v[4:7], v17 offset:15232
	v_add_u32_e32 v12, 0x46000, v10
	v_ashrrev_i32_e32 v13, 31, v12
	v_lshl_add_u64 v[14:15], v[12:13], 0, v[8:9]
	s_waitcnt lgkmcnt(0)
	global_store_dwordx4 v[14:15], v[4:7], off offset:128
	s_nop 1
	s_mov_b64 s[4:5], 0
